# SSD prompt scan: hoisted addressing + bpermute selection + state-part MFMA chain with C=0 (no accumulator zeroing)
# speedup vs baseline: 1.0117x; 1.0009x over previous
.LBB0_706:
	s_or_b64 exec, exec, s[46:47]
	s_lshl_b64 s[44:45], s[44:45], 11
	s_lshl_b64 s[34:35], s[34:35], 1
	s_add_u32 s34, s50, s34
	s_addc_u32 s35, s90, s35
	s_lshl_b32 s41, s41, 5
	s_and_b32 s41, s41, 0x300
	s_waitcnt vmcnt(7)
	v_mul_f32_e32 v2, 0x3fb8aa3b, v4
	s_add_u32 s46, s34, s41
	v_lshlrev_b32_e32 v6, 6, v151
	s_mov_b32 s34, 0x8000
	v_exp_f32_e32 v163, v2
	v_and_b32_e32 v2, 0xfc00, v6
	v_bitop3_b32 v6, v6, s34, v145 bitop3:0x6c
	s_addc_u32 s47, s35, 0
	v_lshlrev_b32_e32 v2, 1, v2
	v_mov_b32_e32 v3, v50
	v_lshlrev_b32_e32 v4, 4, v151
	v_lshlrev_b32_e32 v6, 1, v6
	v_mov_b32_e32 v7, v50
	v_lshl_add_u64 v[2:3], s[46:47], 0, v[2:3]
	v_and_b32_e32 v4, 0xf0, v4
	v_mov_b32_e32 v5, v50
	v_lshl_add_u64 v[6:7], s[46:47], 0, v[6:7]
	v_and_b32_e32 v162, 63, v151
	v_lshl_add_u64 v[2:3], v[2:3], 0, v[4:5]
	v_lshl_add_u64 v[4:5], v[6:7], 0, v[4:5]
	v_ashrrev_i32_e32 v141, 31, v140
	global_load_dwordx4 v[102:105], v[2:3], off
	global_load_dwordx4 v[106:109], v[2:3], off offset:1024
	global_load_dwordx4 v[110:113], v[4:5], off
	global_load_dwordx4 v[114:117], v[4:5], off offset:1024
	v_or_b32_e32 v2, s44, v162
	v_mov_b32_e32 v3, s45
	v_lshl_add_u64 v[4:5], s[44:45], 0, v[140:141]
	v_lshlrev_b64 v[2:3], 7, v[2:3]
	v_lshlrev_b64 v[4:5], 11, v[4:5]
	s_and_b32 s34, s39, 0x3c0
	v_lshl_add_u64 v[2:3], s[20:21], 0, v[2:3]
	v_lshl_add_u64 v[4:5], s[52:53], 0, v[4:5]
	s_lshl_b32 s34, s34, 1
	s_mov_b32 s35, s11
	v_and_b32_e32 v165, 7, v151
	v_lshl_add_u64 v[2:3], v[2:3], 0, s[10:11]
	v_lshl_add_u64 v[4:5], v[4:5], 0, s[34:35]
	v_lshlrev_b32_e32 v6, 4, v165
	v_mov_b32_e32 v7, v50
	s_waitcnt lgkmcnt(0)
	s_barrier
	v_lshl_add_u64 v[4:5], v[4:5], 0, v[6:7]
	global_load_dword v18, v[2:3], off
	global_load_dwordx4 v[118:121], v[4:5], off nt
	s_add_u32 s48, s20, s10
	s_addc_u32 s49, s21, 0
	s_add_u32 s52, s52, s34
	s_addc_u32 s53, s53, 0
	s_add_u32 s54, s4, s10
	s_addc_u32 s55, s5, 0
	s_or_b32 s41, s44, 64
	s_lshl_b32 s34, s39, 1
	s_add_u32 s56, s0, s34
	v_lshlrev_b32_e32 v144, 3, v165
	s_mov_b32 s43, s45
	s_addc_u32 s57, s1, 0
	s_mov_b32 s66, 0
	s_mov_b64 s[70:71], 0
	s_mov_b32 s82, 0
	v_mov_b32_e32 v2, 0
	v_mov_b32_e32 v3, v166
	v_mov_b32_e32 v4, v166
	v_mov_b32_e32 v5, v166
	v_mov_b32_e32 v6, v166
	v_mov_b32_e32 v7, v166
	v_mov_b32_e32 v8, v166
	v_mov_b32_e32 v9, v166
	v_mov_b32_e32 v10, v166
	v_mov_b32_e32 v11, v166
	v_mov_b32_e32 v12, v166
	v_mov_b32_e32 v13, v166
	v_mov_b32_e32 v14, v166
	v_mov_b32_e32 v15, v166
	v_mov_b32_e32 v16, v166
	v_mov_b32_e32 v17, v166
	v_mov_b32_e32 v98, 0
	v_mov_b32_e32 v99, v166
	v_mov_b32_e32 v100, v166
	v_mov_b32_e32 v101, v166
	v_mov_b32_e32 v94, v166
	v_mov_b32_e32 v95, v166
	v_mov_b32_e32 v96, v166
	v_mov_b32_e32 v97, v166
	v_mov_b32_e32 v90, v166
	v_mov_b32_e32 v91, v166
	v_mov_b32_e32 v92, v166
	v_mov_b32_e32 v93, v166
	v_mov_b32_e32 v86, v166
	v_mov_b32_e32 v87, v166
	v_mov_b32_e32 v88, v166
	v_mov_b32_e32 v89, v166
	v_mov_b32_e32 v82, 0
	v_mov_b32_e32 v83, v166
	v_mov_b32_e32 v84, v166
	v_mov_b32_e32 v85, v166
	v_mov_b32_e32 v78, v166
	v_mov_b32_e32 v79, v166
	v_mov_b32_e32 v80, v166
	v_mov_b32_e32 v81, v166
	v_mov_b32_e32 v74, v166
	v_mov_b32_e32 v75, v166
	v_mov_b32_e32 v76, v166
	v_mov_b32_e32 v77, v166
	v_mov_b32_e32 v70, v166
	v_mov_b32_e32 v71, v166
	v_mov_b32_e32 v72, v166
	v_mov_b32_e32 v73, v166
	v_mov_b32_e32 v66, 0
	v_mov_b32_e32 v67, v166
	v_mov_b32_e32 v68, v166
	v_mov_b32_e32 v69, v166
	v_mov_b32_e32 v62, v166
	v_mov_b32_e32 v63, v166
	v_mov_b32_e32 v64, v166
	v_mov_b32_e32 v65, v166
	v_mov_b32_e32 v58, v166
	v_mov_b32_e32 v59, v166
	v_mov_b32_e32 v60, v166
	v_mov_b32_e32 v61, v166
	v_mov_b32_e32 v54, v166
	v_mov_b32_e32 v55, v166
	v_mov_b32_e32 v56, v166
	v_mov_b32_e32 v57, v166
	v_mov_b32_e32 v126, 0
	v_mov_b32_e32 v127, v166
	v_mov_b32_e32 v128, v166
	v_mov_b32_e32 v129, v166
	v_mov_b32_e32 v167, v151
	v_ashrrev_i32_e32 v146, 3, v151
	s_mov_b32 s98, 0x20000
	s_mov_b32 s99, 0
	v_lshlrev_b32_e32 v212, 4, v151
	v_lshrrev_b32_e32 v213, 2, v151
	v_and_b32_e32 v214, 15, v151
	v_bfe_u32 v215, v151, 6, 2
	v_and_b32_e32 v213, 12, v213
	v_bitop3_b32 v213, v213, v214, v215 bitop3:0x36
	v_and_b32_e32 v216, 0x3f00, v212
	v_lshlrev_b32_e32 v213, 4, v213
	v_add3_u32 v196, 0, v216, v213
	v_add_u32_e32 v217, 0x200, v151
	v_lshrrev_b32_e32 v218, 2, v217
	v_and_b32_e32 v218, 12, v218
	v_lshlrev_b32_e32 v219, 4, v217
	v_bitop3_b32 v218, v218, v214, v215 bitop3:0x36
	v_and_b32_e32 v219, 0x3f00, v219
	v_lshlrev_b32_e32 v218, 4, v218
	v_add3_u32 v197, 0, v219, v218
	v_lshlrev_b32_e32 v213, 3, v151
	v_and_b32_e32 v213, 0x78, v213
	v_lshl_add_u32 v216, v213, 1, 0
	v_bfe_u32 v218, v151, 4, 6
	v_mad_u32_u24 v198, v218, s58, v216
	v_lshrrev_b32_e32 v219, 4, v151
	v_bitop3_b32 v219, v219, 32, 63 bitop3:0x6c
	v_mad_u32_u24 v199, v219, s58, v216
	v_or_b32_e32 v204, 64, v218
	v_lshlrev_b32_e32 v204, 11, v204
	v_mov_b32_e32 v205, 0
	v_mov_b32_e32 v217, 0
	v_lshl_add_u64 v[204:205], s[46:47], 0, v[204:205]
	v_or_b32_e32 v206, 64, v219
	v_lshl_add_u64 v[204:205], v[204:205], 0, v[216:217]
	v_lshlrev_b32_e32 v206, 11, v206
	v_mov_b32_e32 v207, 0
	v_and_b32_e32 v200, -4, v146
	v_lshl_add_u64 v[206:207], s[46:47], 0, v[206:207]
	v_add_u32_e32 v202, 0x43, v200
	v_lshl_add_u64 v[206:207], v[206:207], 0, v[216:217]
	v_add_u32_e32 v200, 63, v200
	v_lshlrev_b32_e32 v202, 11, v202
	v_lshlrev_b32_e32 v200, 11, v200
	v_mov_b32_e32 v201, 0
	v_mov_b32_e32 v203, 0
	v_lshl_add_u64 v[200:201], v[142:143], 0, v[200:201]
	v_lshl_add_u64 v[202:203], v[142:143], 0, v[202:203]
	s_mov_b32 s100, 0x2000
	s_mov_b32 s101, 0
	s_mov_b32 s68, s41
	s_mov_b32 s69, s43
	v_mov_b32_e32 v208, v162
	v_mov_b32_e32 v209, 0
	v_mov_b32_e32 v210, v146
	v_mov_b32_e32 v211, 0
	v_lshl_add_u64 v[208:209], s[68:69], 0, v[208:209]
	v_lshl_add_u64 v[210:211], s[68:69], 0, v[210:211]
	v_lshlrev_b64 v[208:209], 7, v[208:209]
	v_lshlrev_b64 v[210:211], 11, v[210:211]
	v_lshl_add_u64 v[208:209], s[48:49], 0, v[208:209]
	v_lshl_add_u64 v[210:211], s[52:53], 0, v[210:211]
	v_and_b32_e32 v220, 0x70, v212
	v_mov_b32_e32 v221, 0
	v_mov_b32_e32 v213, 0
	v_lshl_add_u64 v[210:211], v[210:211], 0, v[220:221]
	v_mov_b32_e32 v212, v146
	v_and_b32_e32 v220, 7, v151
	v_lshl_add_u64 v[212:213], s[44:45], 0, v[212:213]
	v_lshlrev_b32_e32 v222, 4, v220
	v_lshlrev_b64 v[214:215], 7, v[212:213]
	v_lshlrev_b64 v[212:213], 12, v[212:213]
	v_mov_b32_e32 v223, 0
	v_lshl_add_u64 v[214:215], s[54:55], 0, v[214:215]
	v_lshl_add_u64 v[212:213], s[56:57], 0, v[212:213]
	v_lshrrev_b32_e32 v221, 3, v151
	v_lshl_add_u64 v[212:213], v[212:213], 0, v[222:223]
	v_lshlrev_b32_e32 v222, 1, v220
	v_lshlrev_b32_e32 v223, 8, v146
	v_bitop3_b32 v221, v222, v221, 15 bitop3:0x78
	v_add_u32_e32 v224, s63, v223
	v_lshlrev_b32_e32 v225, 5, v220
	v_lshl_add_u32 v216, v221, 4, v224
	s_mov_b32 vcc_lo, 0x1bc00
	v_bfe_u32 v226, v151, 3, 4
	v_add3_u32 v217, vcc_lo, v223, v225
	v_bitop3_b32 v226, v222, v226, 1 bitop3:0x36
	v_xor_b32_e32 v227, v146, v151
	v_lshl_add_u32 v218, v226, 4, v224
	v_lshlrev_b32_e32 v227, 4, v227
	v_lshl_add_u32 v228, v146, 7, s64
	v_and_b32_e32 v227, 0x70, v227
	s_movk_i32 vcc_lo, 0xf000
	v_lshlrev_b32_e32 v231, 1, v151
	v_add3_u32 v219, v228, v227, vcc_lo
	v_and_b32_e32 v231, 62, v231
	v_and_b32_e32 v232, -4, v146
	v_mul_u32_u24_e32 v231, 0x48, v231
	v_lshlrev_b32_e32 v232, 1, v232
	v_lshlrev_b32_e32 v231, 1, v231
	s_nop 0
	v_add3_u32 v229, 0, v231, v232
	v_add3_u32 v230, s60, v231, v232
	v_add_u32_e32 v229, 0xd000, v229
	s_lshl_b32 vcc_lo, s33, 5
	v_lshl_add_u32 v241, v153, 4, vcc_lo
	v_add_u32_e32 v242, 4, v241
	v_add_u32_e32 v243, 8, v241
	v_add_u32_e32 v244, 12, v241
	v_mul_lo_u32 v245, v150, s58
	v_add_u32_e32 v247, s95, v150
	v_lshl_add_u32 v246, v153, 4, s92
	v_mul_lo_u32 v247, v247, s61
	v_lshlrev_b32_e32 v248, 2, v153
	v_lshl_add_u32 v245, v153, 4, v245
	v_lshlrev_b32_e32 v249, 3, v153
	v_add_lshl_u32 v248, v248, s89, 8
	v_lshlrev_b32_e32 v250, 2, v150
	v_add3_u32 v247, s94, v247, v249
	v_add3_u32 v248, s93, v250, v248

.LBB0_718:
	s_or_b64 exec, exec, s[34:35]
	v_sub_f32_e32 v18, s68, v25
	v_mul_f32_e32 v18, 0x3fb8aa3b, v18
	v_exp_f32_e32 v25, v18
	v_lshlrev_b32_e32 v18, 16, v156
	v_and_b32_e32 v19, 0xffff0000, v156
	v_lshlrev_b32_e32 v26, 16, v157
	v_and_b32_e32 v27, 0xffff0000, v157
	v_pk_fma_f32 v[18:19], v[132:133], v[18:19], v[138:139]
	v_mul_f32_e32 v43, v24, v25
	ds_bpermute_b32 v234, v241, v43
	ds_bpermute_b32 v236, v242, v43
	ds_bpermute_b32 v238, v243, v43
	ds_bpermute_b32 v240, v244, v43
	v_lshlrev_b32_e32 v24, 16, v159
	v_and_b32_e32 v25, 0xffff0000, v159
	v_pk_fma_f32 v[18:19], v[134:135], v[26:27], v[18:19]
	v_lshlrev_b32_e32 v28, 16, v158
	v_and_b32_e32 v29, 0xffff0000, v158
	v_pk_fma_f32 v[18:19], v[136:137], v[24:25], v[18:19]
	v_pk_fma_f32 v[18:19], v[130:131], v[28:29], v[18:19]
	v_pk_mul_f32 v[36:37], v[18:19], s[36:37] op_sel_hi:[1,0]
	v_pk_fma_f32 v[26:27], v[132:133], v[26:27], v[138:139]
	v_exp_f32_e32 v36, v36
	v_exp_f32_e32 v37, v37
	v_pk_fma_f32 v[26:27], v[134:135], v[24:25], v[26:27]
	v_pk_add_f32 v[36:37], v[36:37], 1.0 op_sel_hi:[1,0]
	v_lshlrev_b32_e32 v30, 16, v160
	v_rcp_f32_e32 v36, v36
	v_rcp_f32_e32 v37, v37
	v_and_b32_e32 v31, 0xffff0000, v160
	v_pk_fma_f32 v[26:27], v[136:137], v[28:29], v[26:27]
	v_pk_mul_f32 v[18:19], v[18:19], v[36:37]
	v_pk_fma_f32 v[26:27], v[130:131], v[30:31], v[26:27]
	s_waitcnt lgkmcnt(0)
	v_pk_mul_f32 v[36:37], v[18:19], v[234:235] op_sel_hi:[1,0]
	v_pk_mul_f32 v[38:39], v[26:27], s[36:37] op_sel_hi:[1,0]
	v_pk_fma_f32 v[24:25], v[132:133], v[24:25], v[138:139]
	v_exp_f32_e32 v38, v38
	v_exp_f32_e32 v39, v39
	v_pk_fma_f32 v[24:25], v[134:135], v[28:29], v[24:25]
	v_pk_fma_f32 v[28:29], v[132:133], v[28:29], v[138:139]
	v_lshlrev_b32_e32 v32, 16, v161
	v_and_b32_e32 v33, 0xffff0000, v161
	v_pk_add_f32 v[38:39], v[38:39], 1.0 op_sel_hi:[1,0]
	v_pk_fma_f32 v[28:29], v[134:135], v[30:31], v[28:29]
	v_lshlrev_b32_e32 v34, 16, v164
	v_and_b32_e32 v35, 0xffff0000, v164
	v_rcp_f32_e32 v38, v38
	v_rcp_f32_e32 v39, v39
	v_pk_fma_f32 v[28:29], v[136:137], v[32:33], v[28:29]
	v_pk_fma_f32 v[28:29], v[130:131], v[34:35], v[28:29]
	v_pk_fma_f32 v[24:25], v[136:137], v[30:31], v[24:25]
	v_pk_mul_f32 v[30:31], v[28:29], s[36:37] op_sel_hi:[1,0]
	v_exp_f32_e32 v30, v30
	v_exp_f32_e32 v31, v31
	v_pk_mul_f32 v[26:27], v[26:27], v[38:39]
	v_pk_fma_f32 v[24:25], v[130:131], v[32:33], v[24:25]
	v_pk_mul_f32 v[38:39], v[26:27], v[236:237] op_sel_hi:[1,0]
	v_pk_mul_f32 v[40:41], v[24:25], s[36:37] op_sel_hi:[1,0]
	v_exp_f32_e32 v40, v40
	v_exp_f32_e32 v41, v41
	v_pk_add_f32 v[30:31], v[30:31], 1.0 op_sel_hi:[1,0]
	v_rcp_f32_e32 v30, v30
	v_rcp_f32_e32 v31, v31
	v_pk_add_f32 v[40:41], v[40:41], 1.0 op_sel_hi:[1,0]
	v_rcp_f32_e32 v40, v40
	v_rcp_f32_e32 v41, v41
	v_pk_mul_f32 v[28:29], v[28:29], v[30:31]
	v_pk_mul_f32 v[30:31], v[28:29], v[240:241] op_sel_hi:[1,0]
	v_cvt_pk_bf16_f32 v32, v18, v26
	v_pk_mul_f32 v[24:25], v[24:25], v[40:41]
	v_pk_mul_f32 v[40:41], v[24:25], v[238:239] op_sel_hi:[1,0]
	v_cvt_pk_bf16_f32 v33, v24, v28
	v_cvt_pk_bf16_f32 v24, v19, v27
	v_cvt_pk_bf16_f32 v27, v40, v30
	s_cmpk_gt_u32 s82, 0x7bf
	v_cvt_pk_bf16_f32 v25, v25, v29
	v_cvt_pk_bf16_f32 v29, v41, v31
	s_cselect_b64 s[68:69], -1, 0
	v_cvt_pk_bf16_f32 v26, v36, v38
	v_cvt_pk_bf16_f32 v28, v37, v39
	s_and_b64 vcc, exec, s[68:69]
	ds_write2_b64 v229, v[32:33], v[24:25] offset1:18
	ds_write2_b64 v230, v[26:27], v[28:29] offset1:18
	s_cbranch_vccnz .LBB0_720
	global_load_dword v156, v[200:201], off offset:-4096
	global_load_dword v157, v[200:201], off offset:-2048
	global_load_dword v159, v[200:201], off
	global_load_dword v158, v[200:201], off offset:2048
	global_load_dword v160, v[202:203], off offset:-4096
	global_load_dword v161, v[202:203], off offset:-2048
	global_load_dword v164, v[202:203], off
	global_load_dwordx4 v[102:105], v[204:205], off
	global_load_dwordx4 v[106:109], v[204:205], off offset:1024
	global_load_dwordx4 v[110:113], v[206:207], off
	global_load_dwordx4 v[114:117], v[206:207], off offset:1024
	v_lshl_add_u64 v[200:201], v[200:201], 0, s[98:99]
	v_lshl_add_u64 v[202:203], v[202:203], 0, s[98:99]
	v_lshl_add_u64 v[204:205], v[204:205], 0, s[98:99]
	v_lshl_add_u64 v[206:207], v[206:207], 0, s[98:99]
.LBB0_720:
	s_waitcnt lgkmcnt(0)
	s_barrier
	s_waitcnt lgkmcnt(0)
	s_barrier
	s_mov_b64 s[34:35], -1
	s_and_b64 vcc, exec, s[12:13]
	s_cbranch_vccz .LBB0_726
	s_andn2_b64 vcc, exec, s[6:7]
	s_cbranch_vccnz .LBB0_725
	s_mul_i32 s34, s66, 0x4400
	s_add_i32 s34, s27, s34
	v_add_u32_e32 v52, s34, v245
	v_add_u32_e32 v53, s14, v245
	ds_read_b128 v[170:173], v53
	ds_read_b128 v[178:181], v52
	s_waitcnt lgkmcnt(0)
	v_mfma_f32_32x32x16_bf16 v[18:33], v[170:173], v[178:181], 0
	ds_read_b128 v[170:173], v53 offset:32
	ds_read_b128 v[178:181], v52 offset:32
	s_waitcnt lgkmcnt(0)
	v_mfma_f32_32x32x16_bf16 v[34:49], v[170:173], v[178:181], 0
	ds_read_b128 v[170:173], v53 offset:64
	ds_read_b128 v[178:181], v52 offset:64
	s_waitcnt lgkmcnt(0)
	v_mfma_f32_32x32x16_bf16 v[18:33], v[170:173], v[178:181], v[18:33]
	ds_read_b128 v[170:173], v53 offset:96
	ds_read_b128 v[178:181], v52 offset:96
	s_waitcnt lgkmcnt(0)
	v_mfma_f32_32x32x16_bf16 v[34:49], v[170:173], v[178:181], v[34:49]
	ds_read_b128 v[170:173], v53 offset:128
	ds_read_b128 v[178:181], v52 offset:128
	s_waitcnt lgkmcnt(0)
	v_mfma_f32_32x32x16_bf16 v[18:33], v[170:173], v[178:181], v[18:33]
	ds_read_b128 v[170:173], v53 offset:160
	ds_read_b128 v[178:181], v52 offset:160
	s_waitcnt lgkmcnt(0)
	v_mfma_f32_32x32x16_bf16 v[34:49], v[170:173], v[178:181], v[34:49]
	ds_read_b128 v[170:173], v53 offset:192
	ds_read_b128 v[178:181], v52 offset:192
	s_waitcnt lgkmcnt(0)
	v_mfma_f32_32x32x16_bf16 v[18:33], v[170:173], v[178:181], v[18:33]
	ds_read_b128 v[170:173], v53 offset:224
	ds_read_b128 v[178:181], v52 offset:224
	s_waitcnt lgkmcnt(0)
	v_mfma_f32_32x32x16_bf16 v[34:49], v[170:173], v[178:181], v[34:49]
	ds_read_b128 v[170:173], v246
	ds_read_b64 v[52:53], v247 offset:53120
	s_nop 9
	v_pk_add_f32 v[18:19], v[18:19], v[34:35]
	v_pk_add_f32 v[20:21], v[20:21], v[36:37]
	s_waitcnt lgkmcnt(0)
	v_lshlrev_b32_e32 v36, 16, v52
	v_and_b32_e32 v37, 0xffff0000, v52
	v_mul_f32_e32 v34, v155, v36
	v_fmac_f32_e32 v34, v18, v170
	v_mul_f32_e32 v18, v155, v37
	v_lshlrev_b32_e32 v52, 16, v53
	v_and_b32_e32 v53, 0xffff0000, v53
	v_fmac_f32_e32 v18, v19, v171
	ds_write2st64_b32 v248, v34, v18 offset1:1
	v_mul_f32_e32 v18, v155, v52
	v_mul_f32_e32 v19, v155, v53
	v_fmac_f32_e32 v18, v20, v172
	v_fmac_f32_e32 v19, v21, v173
	ds_write2st64_b32 v248, v18, v19 offset0:2 offset1:3
	ds_read_b64 v[34:35], v247 offset:53136
	ds_read_b128 v[18:21], v246 offset:32
	v_pk_add_f32 v[22:23], v[22:23], v[38:39]
	v_pk_add_f32 v[24:25], v[24:25], v[40:41]
	v_pk_add_f32 v[26:27], v[26:27], v[42:43]
	s_waitcnt lgkmcnt(1)
	v_lshlrev_b32_e32 v36, 16, v34
	v_and_b32_e32 v34, 0xffff0000, v34
	v_mul_f32_e32 v36, v155, v36
	s_waitcnt lgkmcnt(0)
	v_fmac_f32_e32 v36, v22, v18
	v_mul_f32_e32 v18, v155, v34
	v_lshlrev_b32_e32 v37, 16, v35
	v_and_b32_e32 v35, 0xffff0000, v35
	v_fmac_f32_e32 v18, v23, v19
	ds_write2st64_b32 v248, v36, v18 offset0:8 offset1:9
	v_mul_f32_e32 v18, v155, v37
	v_mul_f32_e32 v19, v155, v35
	v_fmac_f32_e32 v18, v24, v20
	v_fmac_f32_e32 v19, v25, v21
	ds_write2st64_b32 v248, v18, v19 offset0:10 offset1:11
	ds_read_b64 v[22:23], v247 offset:53152
	ds_read_b128 v[18:21], v246 offset:64
	v_pk_add_f32 v[24:25], v[28:29], v[44:45]
	s_waitcnt lgkmcnt(1)
	v_lshlrev_b32_e32 v28, 16, v22
	v_and_b32_e32 v22, 0xffff0000, v22
	v_mul_f32_e32 v28, v155, v28
	s_waitcnt lgkmcnt(0)
	v_fmac_f32_e32 v28, v26, v18
	v_mul_f32_e32 v18, v155, v22
	v_lshlrev_b32_e32 v29, 16, v23
	v_and_b32_e32 v23, 0xffff0000, v23
	v_fmac_f32_e32 v18, v27, v19
	ds_write2st64_b32 v248, v28, v18 offset0:16 offset1:17
	v_mul_f32_e32 v18, v155, v29
	v_mul_f32_e32 v19, v155, v23
	v_fmac_f32_e32 v18, v24, v20
	v_fmac_f32_e32 v19, v25, v21
	ds_write2st64_b32 v248, v18, v19 offset0:18 offset1:19
	ds_read_b64 v[22:23], v247 offset:53168
	ds_read_b128 v[18:21], v246 offset:96
	v_pk_add_f32 v[26:27], v[30:31], v[46:47]
	v_pk_add_f32 v[24:25], v[32:33], v[48:49]
	s_waitcnt lgkmcnt(1)
	v_lshlrev_b32_e32 v28, 16, v22
	v_and_b32_e32 v22, 0xffff0000, v22
	v_mul_f32_e32 v28, v155, v28
	s_waitcnt lgkmcnt(0)
	v_fmac_f32_e32 v28, v26, v18
	v_mul_f32_e32 v18, v155, v22
	v_lshlrev_b32_e32 v29, 16, v23
	v_and_b32_e32 v23, 0xffff0000, v23
	v_fmac_f32_e32 v18, v27, v19
	ds_write2st64_b32 v248, v28, v18 offset0:24 offset1:25
	v_mul_f32_e32 v18, v155, v29
	v_mul_f32_e32 v19, v155, v23
	v_fmac_f32_e32 v18, v24, v20
	v_fmac_f32_e32 v19, v25, v21
	ds_write2st64_b32 v248, v18, v19 offset0:26 offset1:27
